# dt softplus epilogue spread over all 8 waves (2 log1p chains per lane instead of 8 on 2 waves) + prep row loop waits
# baseline (speedup 1.0000x reference)
; __device__ __forceinline__ void ph_dt_tasks(Frame& F, int layer) {
;     ...
;     for (int it = bid; it < M / 32; it += F.G) {
;         const int row0 = 32 * it + 16 * (wave >> 2);
;         const bf16* ap = pA2 + (size_t)(row0 + r) * D + kq * 512 + 8 * g;
;         bf16x8 av[16];
; #pragma unroll
;         for (int ks = 0; ks < 16; ++ks) av[ks] = *(const bf16x8*)(ap + 32 * ks);
;         f32x4 a0 = {0.f, 0.f, 0.f, 0.f}, a1 = a0;
; #pragma unroll
;         for (int ks = 0; ks < 16; ++ks) { a0 = __builtin_amdgcn_mfma_f32_16x16x32_bf16(av[ks], wv0[ks], a0, 0, 0, 0); a1 = __builtin_amdgcn_mfma_f32_16x16x32_bf16(av[ks], wv1[ks], a1, 0, 0, 0); }
;         red[(wave * 2 + 0) * 64 + lane] = a0; red[(wave * 2 + 1) * 64 + lane] = a1;
;         __syncthreads();
;         if (kq == 0) {
; #pragma unroll
;             for (int k = 1; k < 4; ++k) { a0 += red[((wave + k) * 2 + 0) * 64 + lane]; a1 += red[((wave + k) * 2 + 1) * 64 + lane]; }
; #pragma unroll
;             for (int q = 0; q < 4; ++q) { float* o = pDT + (size_t)(row0 + 4 * g + q) * 32 + r; const float x0 = a0[q] + b0, x1 = a1[q] + b1;
;                 o[0] = fmaxf(x0, 0.f) + log1pf(__expf(-fabsf(x0))); o[16] = fmaxf(x1, 0.f) + log1pf(__expf(-fabsf(x1))); }
.LBB0_770:
	v_add_u32_e32 v132, s2, v140
	v_ashrrev_i32_e32 v133, 31, v132
	v_lshlrev_b64 v[132:133], 12, v[132:133]
	v_lshl_add_u64 v[152:153], v[142:143], 0, v[132:133]
	global_load_dwordx4 v[132:135], v[152:153], off
	global_load_dwordx4 v[146:149], v[152:153], off offset:64
	global_load_dwordx4 v[172:175], v[152:153], off offset:128
	global_load_dwordx4 v[176:179], v[152:153], off offset:192
	global_load_dwordx4 v[180:183], v[152:153], off offset:256
	global_load_dwordx4 v[184:187], v[152:153], off offset:320
	global_load_dwordx4 v[188:191], v[152:153], off offset:384
	global_load_dwordx4 v[192:195], v[152:153], off offset:448
	global_load_dwordx4 v[196:199], v[152:153], off offset:512
	global_load_dwordx4 v[200:203], v[152:153], off offset:576
	global_load_dwordx4 v[204:207], v[152:153], off offset:640
	global_load_dwordx4 v[208:211], v[152:153], off offset:704
	global_load_dwordx4 v[228:231], v[152:153], off offset:768
	global_load_dwordx4 v[232:235], v[152:153], off offset:832
	global_load_dwordx4 v[236:239], v[152:153], off offset:896
	global_load_dwordx4 v[244:247], v[152:153], off offset:960
	s_andn2_b64 vcc, exec, s[0:1]
	s_waitcnt vmcnt(14)
	v_mfma_f32_16x16x32_bf16 v[136:139], v[132:135], v[116:119], 0
	v_mfma_f32_16x16x32_bf16 v[132:135], v[132:135], v[4:7], 0
	v_mfma_f32_16x16x32_bf16 v[136:139], v[146:149], v[12:15], v[136:139]
	v_mfma_f32_16x16x32_bf16 v[132:135], v[146:149], v[8:11], v[132:135]
	s_waitcnt vmcnt(13)
	v_mfma_f32_16x16x32_bf16 v[136:139], v[172:175], v[16:19], v[136:139]
	v_mfma_f32_16x16x32_bf16 v[132:135], v[172:175], v[20:23], v[132:135]
	s_waitcnt vmcnt(12)
	v_mfma_f32_16x16x32_bf16 v[136:139], v[176:179], v[28:31], v[136:139]
	v_mfma_f32_16x16x32_bf16 v[132:135], v[176:179], v[24:27], v[132:135]
	s_waitcnt vmcnt(11)
	v_mfma_f32_16x16x32_bf16 v[136:139], v[180:183], v[32:35], v[136:139]
	v_mfma_f32_16x16x32_bf16 v[132:135], v[180:183], v[36:39], v[132:135]
	s_waitcnt vmcnt(10)
	v_mfma_f32_16x16x32_bf16 v[136:139], v[184:187], v[44:47], v[136:139]
	v_mfma_f32_16x16x32_bf16 v[132:135], v[184:187], v[40:43], v[132:135]
	s_waitcnt vmcnt(9)
	v_mfma_f32_16x16x32_bf16 v[136:139], v[188:191], v[48:51], v[136:139]
	v_mfma_f32_16x16x32_bf16 v[132:135], v[188:191], v[52:55], v[132:135]
	s_waitcnt vmcnt(8)
	v_mfma_f32_16x16x32_bf16 v[136:139], v[192:195], v[60:63], v[136:139]
	v_mfma_f32_16x16x32_bf16 v[132:135], v[192:195], v[56:59], v[132:135]
	s_waitcnt vmcnt(7)
	v_mfma_f32_16x16x32_bf16 v[136:139], v[196:199], v[64:67], v[136:139]
	v_mfma_f32_16x16x32_bf16 v[132:135], v[196:199], v[68:71], v[132:135]
	s_waitcnt vmcnt(6)
	v_mfma_f32_16x16x32_bf16 v[136:139], v[200:203], v[76:79], v[136:139]
	v_mfma_f32_16x16x32_bf16 v[132:135], v[200:203], v[72:75], v[132:135]
	s_waitcnt vmcnt(5)
	v_mfma_f32_16x16x32_bf16 v[136:139], v[204:207], v[80:83], v[136:139]
	v_mfma_f32_16x16x32_bf16 v[132:135], v[204:207], v[84:87], v[132:135]
	s_waitcnt vmcnt(4)
	v_mfma_f32_16x16x32_bf16 v[136:139], v[208:211], v[92:95], v[136:139]
	v_mfma_f32_16x16x32_bf16 v[132:135], v[208:211], v[88:91], v[132:135]
	s_waitcnt vmcnt(3)
	v_mfma_f32_16x16x32_bf16 v[136:139], v[228:231], v[96:99], v[136:139]
	v_mfma_f32_16x16x32_bf16 v[132:135], v[228:231], v[100:103], v[132:135]
	s_waitcnt vmcnt(2)
	v_mfma_f32_16x16x32_bf16 v[136:139], v[232:235], v[108:111], v[136:139]
	v_mfma_f32_16x16x32_bf16 v[132:135], v[232:235], v[104:107], v[132:135]
	s_waitcnt vmcnt(1)
	v_mfma_f32_16x16x32_bf16 v[136:139], v[236:239], v[112:115], v[136:139]
	v_mfma_f32_16x16x32_bf16 v[132:135], v[236:239], v[124:127], v[132:135]
	s_waitcnt vmcnt(0)
	v_mfma_f32_16x16x32_bf16 v[136:139], v[244:247], v[120:123], v[136:139]
	v_mfma_f32_16x16x32_bf16 v[132:135], v[244:247], v[128:131], v[132:135]
	s_nop 6
	ds_write_b128 v2, v[136:139]
	ds_write_b128 v2, v[132:135] offset:1024
	s_waitcnt lgkmcnt(0)
	s_barrier
	s_lshl_b32 s3, s92, 1
	s_lshl_b32 s4, s11, 2
	s_sub_u32 s3, s3, s4
	v_subrev_u32_e32 v146, s3, v2
	ds_read_b32 v152, v146
	ds_read_b32 v153, v146 offset:2048
	ds_read_b32 v154, v146 offset:4096
	ds_read_b32 v155, v146 offset:6144
	ds_read_b32 v156, v146 offset:1024
	ds_read_b32 v157, v146 offset:3072
	ds_read_b32 v158, v146 offset:5120
	ds_read_b32 v159, v146 offset:7168
	v_add_u32_e32 v136, s2, v151
	v_add_u32_e32 v136, s11, v136
	v_ashrrev_i32_e32 v137, 31, v136
	v_lshlrev_b64 v[148:149], 7, v[136:137]
	v_lshl_add_u64 v[148:149], v[144:145], 0, v[148:149]
	s_mov_b32 s3, 0xbfb8aa3b
	s_mov_b32 s4, 0x3f2aaaab
	s_mov_b32 s5, 0x3f317218
	s_mov_b32 s7, 0x7f800000
	s_mov_b32 s8, 0x33800000
	s_waitcnt lgkmcnt(4)
	v_add_f32_e32 v152, v152, v153
	v_add_f32_e32 v152, v152, v154
	v_add_f32_e32 v152, v152, v155
	v_add_f32_e32 v137, v141, v152
	s_waitcnt lgkmcnt(0)
; __device__ __forceinline__ void ph_dt_tasks(Frame& F, int layer) {
;     ...
;         if (kq == 0) {
; #pragma unroll
;             for (int k = 1; k < 4; ++k) { a0 += red[((wave + k) * 2 + 0) * 64 + lane]; a1 += red[((wave + k) * 2 + 1) * 64 + lane]; }
; #pragma unroll
;             for (int q = 0; q < 4; ++q) { float* o = pDT + (size_t)(row0 + 4 * g + q) * 32 + r; const float x0 = a0[q] + b0, x1 = a1[q] + b1;
;                 o[0] = fmaxf(x0, 0.f) + log1pf(__expf(-fabsf(x0))); o[16] = fmaxf(x1, 0.f) + log1pf(__expf(-fabsf(x1))); }
	v_add_f32_e32 v156, v156, v157
	v_add_f32_e32 v156, v156, v158
	v_add_f32_e32 v156, v156, v159
	v_add_f32_e32 v138, v150, v156
	v_max_f32_e32 v146, 0, v137
	v_mul_f32_e64 v137, |v137|, s3
	v_exp_f32_e32 v137, v137
	v_add_f32_e32 v134, v150, v134
	v_add_f32_e32 v154, 1.0, v137
	v_add_f32_e32 v152, -1.0, v154
	v_sub_f32_e32 v153, v152, v154
	v_add_f32_e32 v153, 1.0, v153
	v_sub_f32_e32 v152, v137, v152
	v_add_f32_e32 v155, v152, v153
	v_frexp_mant_f32_e32 v152, v154
	v_cmp_gt_f32_e32 vcc, s4, v152
	v_cvt_f64_f32_e32 v[152:153], v154
	v_frexp_exp_i32_f64_e32 v152, v[152:153]
	v_subbrev_co_u32_e32 v152, vcc, 0, v152, vcc
	v_sub_u32_e32 v153, 0, v152
	v_ldexp_f32 v154, v154, v153
	v_ldexp_f32 v153, v155, v153
	v_add_f32_e32 v155, -1.0, v154
	v_add_f32_e32 v156, 1.0, v155
	v_sub_f32_e32 v156, v154, v156
	v_add_f32_e32 v156, v153, v156
	v_add_f32_e32 v157, v155, v156
	v_sub_f32_e32 v155, v157, v155
	v_sub_f32_e32 v155, v156, v155
	v_add_f32_e32 v156, 1.0, v154
	v_add_f32_e32 v158, -1.0, v156
	v_sub_f32_e32 v154, v154, v158
	v_add_f32_e32 v153, v153, v154
	v_add_f32_e32 v154, v156, v153
	v_sub_f32_e32 v156, v154, v156
	v_sub_f32_e32 v153, v153, v156
	v_rcp_f32_e32 v156, v154
	v_cvt_f32_i32_e32 v152, v152
	v_cmp_neq_f32_e32 vcc, s7, v137
	v_mul_f32_e32 v158, v157, v156
	v_mul_f32_e32 v159, v154, v158
	v_fma_f32 v160, v158, v154, -v159
	v_fmac_f32_e32 v160, v158, v153
	v_add_f32_e32 v161, v159, v160
	v_sub_f32_e32 v162, v157, v161
	v_sub_f32_e32 v157, v157, v162
	v_sub_f32_e32 v159, v161, v159
	v_sub_f32_e32 v157, v157, v161
	v_add_f32_e32 v155, v155, v157
	v_sub_f32_e32 v157, v159, v160
	v_add_f32_e32 v155, v157, v155
	v_add_f32_e32 v157, v162, v155
	v_mul_f32_e32 v159, v156, v157
	v_mul_f32_e32 v160, v154, v159
	v_fma_f32 v154, v159, v154, -v160
	v_fmac_f32_e32 v154, v159, v153
	v_sub_f32_e32 v153, v162, v157
	v_add_f32_e32 v153, v155, v153
	v_add_f32_e32 v155, v160, v154
	v_sub_f32_e32 v161, v157, v155
	v_sub_f32_e32 v157, v157, v161
	v_sub_f32_e32 v160, v155, v160
	v_sub_f32_e32 v155, v157, v155
	v_add_f32_e32 v153, v153, v155
	v_sub_f32_e32 v154, v160, v154
	v_add_f32_e32 v153, v154, v153
	v_add_f32_e32 v154, v158, v159
	v_add_f32_e32 v153, v161, v153
	v_sub_f32_e32 v155, v154, v158
	v_mul_f32_e32 v153, v156, v153
	v_sub_f32_e32 v155, v159, v155
	v_add_f32_e32 v153, v155, v153
	v_mul_f32_e32 v158, 0x3f317218, v152
	v_add_f32_e32 v155, v154, v153
	v_fma_f32 v159, v152, s5, -v158
	v_mul_f32_e32 v156, v155, v155
	v_fmac_f32_e32 v159, 0xb102e308, v152
	v_sub_f32_e32 v152, v155, v154
	v_fmamk_f32 v157, v156, 0x3e9b6dac, v215
	v_sub_f32_e32 v152, v153, v152
	v_add_f32_e32 v153, v158, v159
	v_fmaak_f32 v157, v156, v157, 0x3f2aaada
	v_sub_f32_e32 v154, v153, v158
	v_ldexp_f32 v158, v155, 1
	v_mul_f32_e32 v155, v155, v156
	v_mul_f32_e32 v155, v155, v157
	v_add_f32_e32 v156, v158, v155
	v_sub_f32_e32 v157, v156, v158
	v_ldexp_f32 v152, v152, 1
	v_sub_f32_e32 v155, v155, v157
	v_add_f32_e32 v152, v152, v155
	v_add_f32_e32 v155, v156, v152
	v_sub_f32_e32 v156, v155, v156
	v_sub_f32_e32 v152, v152, v156
	v_add_f32_e32 v156, v153, v155
	v_sub_f32_e32 v157, v156, v153
	v_sub_f32_e32 v158, v156, v157
	v_sub_f32_e32 v154, v159, v154
	v_sub_f32_e32 v153, v153, v158
	v_sub_f32_e32 v155, v155, v157
	v_add_f32_e32 v153, v155, v153
	v_add_f32_e32 v155, v154, v152
	v_sub_f32_e32 v157, v155, v154
	v_sub_f32_e32 v158, v155, v157
	v_sub_f32_e32 v154, v154, v158
	v_sub_f32_e32 v152, v152, v157
	v_add_f32_e32 v153, v155, v153
	v_add_f32_e32 v152, v152, v154
	v_add_f32_e32 v154, v156, v153
	v_sub_f32_e32 v155, v154, v156
	v_sub_f32_e32 v153, v153, v155
	v_add_f32_e32 v152, v152, v153
	v_add_f32_e32 v152, v154, v152
	v_cndmask_b32_e32 v152, v217, v152, vcc
	v_cmp_ngt_f32_e32 vcc, -1.0, v137
	s_nop 1
	v_cndmask_b32_e32 v152, v218, v152, vcc
	v_cmp_neq_f32_e32 vcc, -1.0, v137
	s_nop 1
	v_cndmask_b32_e32 v152, v219, v152, vcc
	v_cmp_lt_f32_e64 vcc, |v137|, s8
	s_nop 1
	v_cndmask_b32_e32 v137, v152, v137, vcc
; __device__ __forceinline__ void ph_dt_tasks(Frame& F, int layer) {
;     ...
;             for (int q = 0; q < 4; ++q) { float* o = pDT + (size_t)(row0 + 4 * g + q) * 32 + r; const float x0 = a0[q] + b0, x1 = a1[q] + b1;
;                 o[0] = fmaxf(x0, 0.f) + log1pf(__expf(-fabsf(x0))); o[16] = fmaxf(x1, 0.f) + log1pf(__expf(-fabsf(x1))); }
;         }
;         __syncthreads();
;     }
	v_add_f32_e32 v137, v146, v137
	global_store_dword v[148:149], v137, off
	v_max_f32_e32 v137, 0, v138
	v_mul_f32_e64 v138, |v138|, s3
	v_exp_f32_e32 v138, v138
	s_nop 0
	v_add_f32_e32 v146, 1.0, v138
	v_add_f32_e32 v152, -1.0, v146
	v_sub_f32_e32 v153, v152, v146
	v_add_f32_e32 v153, 1.0, v153
	v_sub_f32_e32 v152, v138, v152
	v_add_f32_e32 v154, v152, v153
	v_frexp_mant_f32_e32 v152, v146
	v_cmp_gt_f32_e32 vcc, s4, v152
	v_cvt_f64_f32_e32 v[152:153], v146
	v_frexp_exp_i32_f64_e32 v152, v[152:153]
	v_subbrev_co_u32_e32 v152, vcc, 0, v152, vcc
	v_sub_u32_e32 v153, 0, v152
	v_ldexp_f32 v146, v146, v153
	v_ldexp_f32 v153, v154, v153
	v_add_f32_e32 v154, -1.0, v146
	v_add_f32_e32 v155, 1.0, v154
	v_sub_f32_e32 v155, v146, v155
	v_add_f32_e32 v155, v153, v155
	v_add_f32_e32 v156, v154, v155
	v_sub_f32_e32 v154, v156, v154
	v_sub_f32_e32 v154, v155, v154
	v_add_f32_e32 v155, 1.0, v146
	v_add_f32_e32 v157, -1.0, v155
	v_sub_f32_e32 v146, v146, v157
	v_add_f32_e32 v146, v153, v146
	v_add_f32_e32 v153, v155, v146
	v_sub_f32_e32 v155, v153, v155
	v_sub_f32_e32 v146, v146, v155
	v_rcp_f32_e32 v155, v153
	v_cvt_f32_i32_e32 v152, v152
	v_cmp_neq_f32_e32 vcc, s7, v138
	v_mul_f32_e32 v157, v156, v155
	v_mul_f32_e32 v158, v153, v157
	v_fma_f32 v159, v157, v153, -v158
	v_fmac_f32_e32 v159, v157, v146
	v_add_f32_e32 v160, v158, v159
	v_sub_f32_e32 v161, v156, v160
	v_sub_f32_e32 v156, v156, v161
	v_sub_f32_e32 v158, v160, v158
	v_sub_f32_e32 v156, v156, v160
	v_add_f32_e32 v154, v154, v156
	v_sub_f32_e32 v156, v158, v159
	v_add_f32_e32 v154, v156, v154
	v_add_f32_e32 v156, v161, v154
	v_mul_f32_e32 v158, v155, v156
	v_mul_f32_e32 v159, v153, v158
	v_fma_f32 v153, v158, v153, -v159
	v_fmac_f32_e32 v153, v158, v146
	v_sub_f32_e32 v146, v161, v156
	v_add_f32_e32 v146, v154, v146
	v_add_f32_e32 v154, v159, v153
	v_sub_f32_e32 v160, v156, v154
	v_sub_f32_e32 v156, v156, v160
	v_sub_f32_e32 v159, v154, v159
	v_sub_f32_e32 v154, v156, v154
	v_add_f32_e32 v146, v146, v154
	v_sub_f32_e32 v153, v159, v153
	v_add_f32_e32 v146, v153, v146
	v_add_f32_e32 v153, v157, v158
	v_add_f32_e32 v146, v160, v146
	v_sub_f32_e32 v154, v153, v157
	v_mul_f32_e32 v146, v155, v146
	v_sub_f32_e32 v154, v158, v154
	v_add_f32_e32 v146, v154, v146
	v_mul_f32_e32 v157, 0x3f317218, v152
	v_add_f32_e32 v154, v153, v146
	v_fma_f32 v158, v152, s5, -v157
	v_mul_f32_e32 v155, v154, v154
	v_fmac_f32_e32 v158, 0xb102e308, v152
	v_sub_f32_e32 v152, v154, v153
	v_fmamk_f32 v156, v155, 0x3e9b6dac, v215
	v_sub_f32_e32 v146, v146, v152
	v_add_f32_e32 v152, v157, v158
	v_fmaak_f32 v156, v155, v156, 0x3f2aaada
	v_sub_f32_e32 v153, v152, v157
	v_ldexp_f32 v157, v154, 1
	v_mul_f32_e32 v154, v154, v155
	v_mul_f32_e32 v154, v154, v156
	v_add_f32_e32 v155, v157, v154
	v_sub_f32_e32 v156, v155, v157
	v_ldexp_f32 v146, v146, 1
	v_sub_f32_e32 v154, v154, v156
	v_add_f32_e32 v146, v146, v154
	v_add_f32_e32 v154, v155, v146
	v_sub_f32_e32 v155, v154, v155
	v_sub_f32_e32 v146, v146, v155
	v_add_f32_e32 v155, v152, v154
	v_sub_f32_e32 v156, v155, v152
	v_sub_f32_e32 v157, v155, v156
	v_sub_f32_e32 v153, v158, v153
	v_sub_f32_e32 v152, v152, v157
	v_sub_f32_e32 v154, v154, v156
	v_add_f32_e32 v152, v154, v152
	v_add_f32_e32 v154, v153, v146
	v_sub_f32_e32 v156, v154, v153
	v_sub_f32_e32 v157, v154, v156
	v_sub_f32_e32 v153, v153, v157
	v_sub_f32_e32 v146, v146, v156
	v_add_f32_e32 v152, v154, v152
	v_add_f32_e32 v146, v146, v153
	v_add_f32_e32 v153, v155, v152
	v_sub_f32_e32 v154, v153, v155
	v_sub_f32_e32 v152, v152, v154
	v_add_f32_e32 v146, v146, v152
	v_add_f32_e32 v146, v153, v146
	v_cndmask_b32_e32 v146, v217, v146, vcc
	v_cmp_ngt_f32_e32 vcc, -1.0, v138
	s_nop 1
	v_cndmask_b32_e32 v146, v218, v146, vcc
	v_cmp_neq_f32_e32 vcc, -1.0, v138
	s_nop 1
	v_cndmask_b32_e32 v146, v219, v146, vcc
	v_cmp_lt_f32_e64 vcc, |v138|, s8
	s_nop 1
	v_cndmask_b32_e32 v138, v146, v138, vcc
	v_add_f32_e32 v137, v137, v138
	global_store_dword v[148:149], v137, off offset:64
	s_branch .LBB0_769

; __device__ __forceinline__ unsigned pk2(float lo, float hi) { return cvtpk(lo, hi); }
; __device__ __forceinline__ float silu(float x) { return x * __builtin_amdgcn_rcpf(1.0f + __builtin_amdgcn_exp2f(x * -1.44269504089f)); }
; __device__ __forceinline__ void ph_prep(Frame& F, int layer) {
;     ...
;     const int ch16 = lane & 15, fb = 8 * (ch16 & 3); const bool second = (ch16 & 4) != 0, colpart = (ch16 & 8) != 0;
;     v4u qc, kc, u0c[3], u1c[3], u2c[3], qn, kn, u0n[3], u1n[3], u2n[3];
;     ...
;     qn = kn = (v4u){0u, 0u, 0u, 0u};
; #pragma unroll
;     for (int r = 0; r < 3; ++r) u0n[r] = u1n[r] = u2n[r] = (v4u){0u, 0u, 0u, 0u};
;     if (gw < M) PREP_LOAD(gw, qc, kc, u0c, u1c, u2c);
;     ...
;         for (int r = 0; r < 3; ++r) {
;             const int ch = 8 * lane + 512 * r;
;             unsigned ow[4];
; #pragma unroll
;             for (int e2 = 0; e2 < 4; ++e2) { const int hf = e2 >> 1, k0 = 2 * (e2 & 1);
;                 const float ylo = w0[r][hf][k0] * bflo(u0c[r][e2]) + w1[r][hf][k0] * bflo(u1c[r][e2]) + w2[r][hf][k0] * bflo(u2c[r][e2]) + wb[r][hf][k0];
;                 const float yhi = w0[r][hf][k0 + 1] * bfhi(u0c[r][e2]) + w1[r][hf][k0 + 1] * bfhi(u1c[r][e2]) + w2[r][hf][k0 + 1] * bfhi(u2c[r][e2]) + wb[r][hf][k0 + 1];
;                 ow[e2] = pk2(silu(ylo), silu(yhi)); }
.LBB0_794:
	v_and_b32_e32 v135, 24, v135
	v_and_b32_e32 v136, 4, v132
	v_and_b32_e32 v132, 8, v132
	v_lshl_add_u32 v228, v135, 2, 0
	v_and_b32_e32 v135, 64, v216
	v_cmp_eq_u32_e64 s[10:11], 0, v132
	s_mov_b32 s13, s93
	s_mov_b32 s9, s93
	s_mov_b32 s3, s93
	v_xor_b32_e32 v132, 4, v216
	v_add_u32_e32 v135, 64, v135
	s_lshl_b64 s[6:7], s[12:13], 20
	s_lshl_b64 s[12:13], s[8:9], 20
	s_lshl_b64 s[8:9], s[2:3], 20
	v_cmp_lt_i32_e32 vcc, v132, v135
	s_movk_i32 s2, 0x500
	s_lshl_b64 s[14:15], s[18:19], 9
	v_cndmask_b32_e32 v132, v216, v132, vcc
	v_cmp_gt_u32_e32 vcc, s2, v134
	s_add_u32 s2, s12, s14
	s_addc_u32 s3, s13, s15
	v_lshlrev_b32_e32 v229, 2, v132
	v_mov_b32_e32 v132, s23
	v_mov_b32_e32 v135, s22
	s_add_u32 s2, s78, s2
	v_cmp_eq_u32_e64 s[0:1], 0, v136
	v_cndmask_b32_e32 v134, v132, v135, vcc
	v_mov_b32_e32 v135, v3
	v_mov_b32_e32 v132, 0xfffff600
	v_mov_b32_e32 v136, 0xfffff800
	s_addc_u32 s3, s79, s3
	v_readlane_b32 s12, v253, 13
	v_lshlrev_b64 v[134:135], 20, v[134:135]
	v_cndmask_b32_e32 v242, v132, v136, vcc
	s_add_u32 s12, s12, s14
	v_readlane_b32 s13, v253, 14
	v_mov_b32_e32 v196, v100
	v_mov_b32_e32 v197, v64
	v_mov_b32_e32 v64, v101
	v_lshl_add_u64 v[100:101], v[242:243], 0, v[134:135]
	s_addc_u32 s13, s13, s15
	v_lshl_add_u64 v[200:201], s[12:13], 0, v[100:101]
	s_lshl_b64 s[12:13], s[18:19], 11
	s_add_u32 s8, s8, s12
	s_addc_u32 s9, s9, s13
	v_readlane_b32 s12, v253, 15
	s_add_u32 s12, s12, s8
	v_readlane_b32 s8, v253, 16
	s_addc_u32 s13, s8, s9
	s_lshl_b64 s[8:9], s[18:19], 10
	s_add_u32 s6, s6, s8
	s_addc_u32 s7, s7, s9
	v_mov_b32_e32 v144, v3
	v_mov_b32_e32 v145, v3
	v_mov_b32_e32 v174, v130
	v_mov_b32_e32 v175, v14
	v_mov_b32_e32 v14, v131
	v_mov_b32_e32 v176, v128
	v_mov_b32_e32 v177, v12
	v_mov_b32_e32 v12, v129
	v_mov_b32_e32 v186, v114
	v_mov_b32_e32 v187, v42
	v_mov_b32_e32 v42, v115
	v_mov_b32_e32 v188, v112
	v_mov_b32_e32 v189, v40
	v_mov_b32_e32 v40, v113
	v_mov_b32_e32 v190, v110
	v_mov_b32_e32 v191, v62
	v_mov_b32_e32 v62, v111
	v_mov_b32_e32 v192, v108
	v_mov_b32_e32 v193, v60
	v_mov_b32_e32 v60, v109
	v_mov_b32_e32 v194, v102
	v_mov_b32_e32 v195, v66
	v_mov_b32_e32 v66, v103
	s_add_u32 s14, s78, s6
	v_mov_b32_e32 v146, v3
	v_mov_b32_e32 v147, v3
	v_mov_b32_e32 v136, 0
	v_mov_b64_e32 v[128:129], v[144:145]
	v_mov_b64_e32 v[112:113], v[144:145]
	v_mov_b64_e32 v[100:101], v[144:145]
	v_mov_b64_e32 v[108:109], v[144:145]
	v_cmp_gt_u32_e64 s[4:5], 32, v133
	v_mov_b32_e32 v178, v126
	v_mov_b32_e32 v179, v18
	v_mov_b32_e32 v18, v127
	v_mov_b32_e32 v180, v124
	v_mov_b32_e32 v181, v16
	v_mov_b32_e32 v16, v125
	v_mov_b32_e32 v182, v118
	v_mov_b32_e32 v183, v38
	v_mov_b32_e32 v38, v119
	v_mov_b32_e32 v184, v116
	v_mov_b32_e32 v185, v36
	v_mov_b32_e32 v36, v117
	v_lshlrev_b32_e32 v198, 4, v133
	v_mov_b32_e32 v199, v3
	s_addc_u32 s15, s79, s7
	v_mov_b64_e32 v[130:131], v[146:147]
	v_mov_b64_e32 v[114:115], v[146:147]
	v_mov_b64_e32 v[102:103], v[146:147]
	v_mov_b64_e32 v[110:111], v[146:147]
	v_mov_b32_e32 v137, v136
	v_mov_b32_e32 v138, v136
	v_mov_b32_e32 v139, v136
	v_mov_b32_e32 v124, v136
	v_mov_b32_e32 v125, v136
	v_mov_b32_e32 v126, v136
	v_mov_b32_e32 v127, v136
	v_mov_b32_e32 v116, v136
	v_mov_b32_e32 v117, v136
	v_mov_b32_e32 v118, v136
	v_mov_b32_e32 v119, v136
	v_mov_b32_e32 v160, v136
	v_mov_b32_e32 v161, v136
	v_mov_b32_e32 v162, v136
	v_mov_b32_e32 v163, v136
	v_mov_b32_e32 v148, v136
	v_mov_b32_e32 v149, v136
	v_mov_b32_e32 v150, v136
	v_mov_b32_e32 v151, v136
	v_mov_b32_e32 v132, v136
	v_mov_b32_e32 v133, v136
	v_mov_b32_e32 v134, v136
	v_mov_b32_e32 v135, v136
	s_nop 0
	s_waitcnt vmcnt(0)
	s_branch .LBB0_796
.LBB0_795:
	s_or_b64 exec, exec, s[6:7]
	v_lshlrev_b32_e32 v152, 16, v140
	v_lshlrev_b32_e32 v153, 16, v104
	v_lshlrev_b32_e32 v154, 16, v120
	v_pk_mul_f32 v[152:153], v[180:181], v[152:153]
	v_and_b32_e32 v120, 0xffff0000, v120
	v_fma_f32 v153, v8, v154, v153
	v_add_f32_e32 v152, v152, v153
	v_add_f32_e32 v154, v24, v152
	v_and_b32_e32 v153, 0xffff0000, v104
	v_and_b32_e32 v152, 0xffff0000, v140
	v_mul_f32_e32 v104, 0xbfb8aa3b, v154
	v_pk_mul_f32 v[152:153], v[16:17], v[152:153]
	v_exp_f32_e32 v104, v104
	v_fma_f32 v120, v9, v120, v153
	v_add_f32_e32 v120, v152, v120
	v_add_f32_e32 v120, v25, v120
	v_add_f32_e32 v104, 1.0, v104
	v_mul_f32_e32 v140, 0xbfb8aa3b, v120
	v_rcp_f32_e32 v104, v104
	v_exp_f32_e32 v140, v140
	v_lshlrev_b32_e32 v152, 16, v141
	v_lshlrev_b32_e32 v153, 16, v105
	v_mul_f32_e32 v154, v154, v104
	v_add_f32_e32 v104, 1.0, v140
	v_rcp_f32_e32 v140, v104
	v_lshlrev_b32_e32 v104, 16, v121
	v_pk_mul_f32 v[152:153], v[178:179], v[152:153]
	v_and_b32_e32 v105, 0xffff0000, v105
	v_fma_f32 v104, v10, v104, v153
	v_add_f32_e32 v104, v152, v104
	v_add_f32_e32 v152, v26, v104
	v_and_b32_e32 v104, 0xffff0000, v141
	v_mul_f32_e32 v141, 0xbfb8aa3b, v152
	v_exp_f32_e32 v141, v141
	v_and_b32_e32 v121, 0xffff0000, v121
	v_pk_mul_f32 v[104:105], v[18:19], v[104:105]
	v_readlane_b32 s6, v253, 11
	v_fma_f32 v105, v11, v121, v105
	v_add_f32_e32 v104, v104, v105
	v_add_f32_e32 v105, v27, v104
	v_add_f32_e32 v104, 1.0, v141
	v_rcp_f32_e32 v121, v104
	v_mul_f32_e32 v104, 0xbfb8aa3b, v105
	v_exp_f32_e32 v141, v104
	v_mul_f32_e32 v104, v120, v140
	v_mul_f32_e32 v140, v152, v121
	v_lshlrev_b32_e32 v121, 16, v106
	v_add_f32_e32 v120, 1.0, v141
	v_rcp_f32_e32 v141, v120
	v_lshlrev_b32_e32 v120, 16, v142
	v_lshlrev_b32_e32 v152, 16, v122
	v_pk_mul_f32 v[120:121], v[176:177], v[120:121]
	v_and_b32_e32 v122, 0xffff0000, v122
	v_fma_f32 v121, v4, v152, v121
	v_add_f32_e32 v120, v120, v121
	v_add_f32_e32 v152, v20, v120
	v_and_b32_e32 v121, 0xffff0000, v106
	v_and_b32_e32 v120, 0xffff0000, v142
; __device__ __forceinline__ unsigned pk2(float lo, float hi) { return cvtpk(lo, hi); }
; __device__ __forceinline__ float silu(float x) { return x * __builtin_amdgcn_rcpf(1.0f + __builtin_amdgcn_exp2f(x * -1.44269504089f)); }
; __device__ __forceinline__ void ph_prep(Frame& F, int layer) {
;     ...
;         for (int r = 0; r < 3; ++r) {
;             const int ch = 8 * lane + 512 * r;
;             unsigned ow[4];
; #pragma unroll
;             for (int e2 = 0; e2 < 4; ++e2) { const int hf = e2 >> 1, k0 = 2 * (e2 & 1);
;                 const float ylo = w0[r][hf][k0] * bflo(u0c[r][e2]) + w1[r][hf][k0] * bflo(u1c[r][e2]) + w2[r][hf][k0] * bflo(u2c[r][e2]) + wb[r][hf][k0];
;                 const float yhi = w0[r][hf][k0 + 1] * bfhi(u0c[r][e2]) + w1[r][hf][k0 + 1] * bfhi(u1c[r][e2]) + w2[r][hf][k0 + 1] * bfhi(u2c[r][e2]) + wb[r][hf][k0 + 1];
;                 ow[e2] = pk2(silu(ylo), silu(yhi)); }
;             const v4u o = {ow[0], ow[1], ow[2], ow[3]};
;             if (ch < 1024) *(v4u*)(pSX + (size_t)row * 1024 + ch) = o;
;             else if (ch < 1280) *(v4u*)(pSB + (size_t)row * 256 + (ch - 1024)) = o;
;             else *(v4u*)(pSC + (size_t)row * 256 + (ch - 1280)) = o;
	v_pk_mul_f32 v[120:121], v[12:13], v[120:121]
	v_mul_f32_e32 v106, 0xbfb8aa3b, v152
	v_exp_f32_e32 v106, v106
	v_fma_f32 v121, v5, v122, v121
	v_add_f32_e32 v120, v120, v121
	v_add_f32_e32 v122, v21, v120
	v_mul_f32_e32 v120, 0xbfb8aa3b, v122
	v_add_f32_e32 v106, 1.0, v106
	v_exp_f32_e32 v120, v120
	v_rcp_f32_e32 v106, v106
	v_mul_f32_e32 v105, v105, v141
	v_lshlrev_b32_e32 v121, 16, v107
	v_add_f32_e32 v141, 1.0, v120
	v_lshlrev_b32_e32 v120, 16, v143
	v_cvt_pk_bf16_f32 v105, v140, v105
	v_mul_f32_e32 v140, v152, v106
	v_lshlrev_b32_e32 v106, 16, v123
	v_pk_mul_f32 v[120:121], v[174:175], v[120:121]
	v_and_b32_e32 v107, 0xffff0000, v107
	v_fma_f32 v106, v6, v106, v121
	v_add_f32_e32 v106, v120, v106
	v_add_f32_e32 v120, v22, v106
	v_and_b32_e32 v106, 0xffff0000, v143
	v_and_b32_e32 v121, 0xffff0000, v123
	v_pk_mul_f32 v[106:107], v[14:15], v[106:107]
	v_rcp_f32_e32 v123, v141
	v_fma_f32 v107, v7, v121, v107
	v_add_f32_e32 v106, v106, v107
	v_add_f32_e32 v107, v23, v106
	v_mul_f32_e32 v106, 0xbfb8aa3b, v120
	v_exp_f32_e32 v106, v106
	v_mul_f32_e32 v121, 0xbfb8aa3b, v107
	v_exp_f32_e32 v121, v121
	v_cvt_pk_bf16_f32 v104, v154, v104
	v_add_f32_e32 v106, 1.0, v106
	v_rcp_f32_e32 v141, v106
	v_add_f32_e32 v106, 1.0, v121
	v_rcp_f32_e32 v121, v106
	v_mul_f32_e32 v106, v122, v123
	v_mul_f32_e32 v120, v120, v141
	v_lshlrev_b32_e32 v122, 16, v92
	v_mul_f32_e32 v107, v107, v121
	v_cvt_pk_bf16_f32 v107, v120, v107
	v_lshlrev_b32_e32 v120, 16, v96
	v_lshlrev_b32_e32 v121, 16, v88
	v_pk_mul_f32 v[120:121], v[188:189], v[120:121]
	v_and_b32_e32 v92, 0xffff0000, v92
	v_fma_f32 v121, v32, v122, v121
	v_add_f32_e32 v120, v120, v121
	v_add_f32_e32 v122, v48, v120
	v_and_b32_e32 v121, 0xffff0000, v88
	v_and_b32_e32 v120, 0xffff0000, v96
	v_mul_f32_e32 v88, 0xbfb8aa3b, v122
	v_pk_mul_f32 v[120:121], v[40:41], v[120:121]
	v_exp_f32_e32 v88, v88
	v_fma_f32 v92, v33, v92, v121
	v_add_f32_e32 v92, v120, v92
	v_add_f32_e32 v92, v49, v92
	v_add_f32_e32 v88, 1.0, v88
	v_mul_f32_e32 v96, 0xbfb8aa3b, v92
	v_rcp_f32_e32 v88, v88
	v_exp_f32_e32 v96, v96
	v_cvt_pk_bf16_f32 v106, v140, v106
	v_lshl_add_u64 v[120:121], s[12:13], 0, v[198:199]
	global_store_dwordx4 v[120:121], v[104:107], off offset:-1024
	v_readlane_b32 s7, v253, 12
	s_add_u32 s2, s2, s6
	v_mul_f32_e32 v106, v122, v88
	v_add_f32_e32 v88, 1.0, v96
	v_lshlrev_b32_e32 v104, 16, v97
	v_lshlrev_b32_e32 v105, 16, v89
	v_rcp_f32_e32 v96, v88
	v_lshlrev_b32_e32 v88, 16, v93
	v_pk_mul_f32 v[104:105], v[186:187], v[104:105]
	v_and_b32_e32 v89, 0xffff0000, v89
	v_fma_f32 v88, v34, v88, v105
	v_add_f32_e32 v88, v104, v88
	v_add_f32_e32 v104, v50, v88
	v_and_b32_e32 v88, 0xffff0000, v97
	v_mul_f32_e32 v97, 0xbfb8aa3b, v104
	v_exp_f32_e32 v97, v97
	v_and_b32_e32 v93, 0xffff0000, v93
	v_pk_mul_f32 v[88:89], v[42:43], v[88:89]
	s_addc_u32 s3, s3, s7
	v_fma_f32 v89, v35, v93, v89
	v_add_f32_e32 v88, v88, v89
	v_add_f32_e32 v89, v51, v88
	v_add_f32_e32 v88, 1.0, v97
	v_rcp_f32_e32 v93, v88
	v_mul_f32_e32 v88, 0xbfb8aa3b, v89
	v_exp_f32_e32 v97, v88
	v_mul_f32_e32 v88, v92, v96
	v_mul_f32_e32 v96, v104, v93
	v_lshlrev_b32_e32 v93, 16, v90
	v_add_f32_e32 v92, 1.0, v97
	v_rcp_f32_e32 v97, v92
	v_lshlrev_b32_e32 v92, 16, v98
	v_lshlrev_b32_e32 v104, 16, v94
	v_pk_mul_f32 v[92:93], v[184:185], v[92:93]
	v_and_b32_e32 v94, 0xffff0000, v94
	v_fma_f32 v93, v28, v104, v93
	v_add_f32_e32 v92, v92, v93
	v_add_f32_e32 v104, v44, v92
	v_and_b32_e32 v93, 0xffff0000, v90
	v_and_b32_e32 v92, 0xffff0000, v98
	v_pk_mul_f32 v[92:93], v[36:37], v[92:93]
	v_mul_f32_e32 v90, 0xbfb8aa3b, v104
	v_exp_f32_e32 v90, v90
	v_fma_f32 v93, v29, v94, v93
	v_add_f32_e32 v92, v92, v93
	v_add_f32_e32 v94, v45, v92
	v_mul_f32_e32 v92, 0xbfb8aa3b, v94
	v_add_f32_e32 v90, 1.0, v90
	v_exp_f32_e32 v92, v92
	v_rcp_f32_e32 v90, v90
	v_mul_f32_e32 v89, v89, v97
	v_lshlrev_b32_e32 v93, 16, v91
	v_add_f32_e32 v97, 1.0, v92
	v_lshlrev_b32_e32 v92, 16, v99
	v_cvt_pk_bf16_f32 v89, v96, v89
	v_mul_f32_e32 v96, v104, v90
	v_lshlrev_b32_e32 v90, 16, v95
	v_pk_mul_f32 v[92:93], v[182:183], v[92:93]
	v_and_b32_e32 v91, 0xffff0000, v91
	v_fma_f32 v90, v30, v90, v93
	v_add_f32_e32 v90, v92, v90
	v_add_f32_e32 v92, v46, v90
	v_and_b32_e32 v90, 0xffff0000, v99
	v_and_b32_e32 v93, 0xffff0000, v95
	v_pk_mul_f32 v[90:91], v[38:39], v[90:91]
	v_rcp_f32_e32 v95, v97
	v_fma_f32 v91, v31, v93, v91
	v_add_f32_e32 v90, v90, v91
	v_add_f32_e32 v91, v47, v90
	v_mul_f32_e32 v90, 0xbfb8aa3b, v92
	v_exp_f32_e32 v90, v90
	v_mul_f32_e32 v93, 0xbfb8aa3b, v91
	v_exp_f32_e32 v93, v93
	v_cvt_pk_bf16_f32 v88, v106, v88
	v_add_f32_e32 v90, 1.0, v90
	v_rcp_f32_e32 v97, v90
	v_add_f32_e32 v90, 1.0, v93
	v_rcp_f32_e32 v93, v90
	v_mul_f32_e32 v90, v94, v95
	v_mul_f32_e32 v94, v92, v97
	v_lshlrev_b32_e32 v92, 16, v84
	v_mul_f32_e32 v91, v91, v93
	v_lshlrev_b32_e32 v93, 16, v76
	v_lshlrev_b32_e32 v95, 16, v80
	v_pk_mul_f32 v[92:93], v[196:197], v[92:93]
	v_and_b32_e32 v80, 0xffff0000, v80
	v_fma_f32 v93, v56, v95, v93
	v_add_f32_e32 v92, v92, v93
	v_add_f32_e32 v95, v72, v92
	v_and_b32_e32 v93, 0xffff0000, v76
	v_and_b32_e32 v92, 0xffff0000, v84
	v_mul_f32_e32 v76, 0xbfb8aa3b, v95
	v_pk_mul_f32 v[92:93], v[64:65], v[92:93]
	v_exp_f32_e32 v76, v76
	v_fma_f32 v80, v57, v80, v93
	v_add_f32_e32 v80, v92, v80
	v_add_f32_e32 v80, v73, v80
	v_add_f32_e32 v76, 1.0, v76
	v_mul_f32_e32 v84, 0xbfb8aa3b, v80
	v_rcp_f32_e32 v76, v76
	v_exp_f32_e32 v84, v84
	v_cvt_pk_bf16_f32 v90, v96, v90
	v_cvt_pk_bf16_f32 v91, v94, v91
	global_store_dwordx4 v[120:121], v[88:91], off
	s_waitcnt vmcnt(3)
; __device__ __forceinline__ unsigned pk2(float lo, float hi) { return cvtpk(lo, hi); }
; __device__ __forceinline__ float silu(float x) { return x * __builtin_amdgcn_rcpf(1.0f + __builtin_amdgcn_exp2f(x * -1.44269504089f)); }
; __device__ __forceinline__ void ph_prep(Frame& F, int layer) {
;     ...
;             for (int e2 = 0; e2 < 4; ++e2) { const int hf = e2 >> 1, k0 = 2 * (e2 & 1);
;                 const float ylo = w0[r][hf][k0] * bflo(u0c[r][e2]) + w1[r][hf][k0] * bflo(u1c[r][e2]) + w2[r][hf][k0] * bflo(u2c[r][e2]) + wb[r][hf][k0];
;                 const float yhi = w0[r][hf][k0 + 1] * bfhi(u0c[r][e2]) + w1[r][hf][k0 + 1] * bfhi(u1c[r][e2]) + w2[r][hf][k0 + 1] * bfhi(u2c[r][e2]) + wb[r][hf][k0 + 1];
;                 ow[e2] = pk2(silu(ylo), silu(yhi)); }
;             const v4u o = {ow[0], ow[1], ow[2], ow[3]};
;             if (ch < 1024) *(v4u*)(pSX + (size_t)row * 1024 + ch) = o;
;             else if (ch < 1280) *(v4u*)(pSB + (size_t)row * 256 + (ch - 1024)) = o;
;             else *(v4u*)(pSC + (size_t)row * 256 + (ch - 1280)) = o;
;         }
;         qc = qn; kc = kn;
; #pragma unroll
;         for (int r = 0; r < 3; ++r) { u0c[r] = u0n[r]; u1c[r] = u1n[r]; u2c[r] = u2n[r]; }
	v_mov_b64_e32 v[104:105], v[112:113]
	v_mov_b64_e32 v[158:159], v[102:103]
	v_mul_f32_e32 v90, v95, v76
	v_add_f32_e32 v76, 1.0, v84
	v_lshlrev_b32_e32 v88, 16, v85
	v_lshlrev_b32_e32 v89, 16, v77
	v_rcp_f32_e32 v84, v76
	v_lshlrev_b32_e32 v76, 16, v81
	v_pk_mul_f32 v[88:89], v[194:195], v[88:89]
	v_and_b32_e32 v77, 0xffff0000, v77
	v_fma_f32 v76, v58, v76, v89
	v_add_f32_e32 v76, v88, v76
	v_add_f32_e32 v88, v74, v76
	v_and_b32_e32 v76, 0xffff0000, v85
	v_mul_f32_e32 v85, 0xbfb8aa3b, v88
	v_exp_f32_e32 v85, v85
	v_and_b32_e32 v81, 0xffff0000, v81
	v_pk_mul_f32 v[76:77], v[66:67], v[76:77]
	v_mov_b64_e32 v[154:155], v[110:111]
	v_fma_f32 v77, v59, v81, v77
	v_add_f32_e32 v76, v76, v77
	v_add_f32_e32 v77, v75, v76
	v_add_f32_e32 v76, 1.0, v85
	v_rcp_f32_e32 v81, v76
	v_mul_f32_e32 v76, 0xbfb8aa3b, v77
	v_exp_f32_e32 v85, v76
	v_mul_f32_e32 v76, v80, v84
	v_mul_f32_e32 v84, v88, v81
	v_lshlrev_b32_e32 v81, 16, v78
	v_add_f32_e32 v80, 1.0, v85
	v_rcp_f32_e32 v85, v80
	v_lshlrev_b32_e32 v80, 16, v86
	v_lshlrev_b32_e32 v88, 16, v82
	v_pk_mul_f32 v[80:81], v[192:193], v[80:81]
	v_and_b32_e32 v82, 0xffff0000, v82
	v_fma_f32 v81, v52, v88, v81
	v_add_f32_e32 v80, v80, v81
	v_add_f32_e32 v88, v68, v80
	v_and_b32_e32 v81, 0xffff0000, v78
	v_and_b32_e32 v80, 0xffff0000, v86
	v_pk_mul_f32 v[80:81], v[60:61], v[80:81]
	v_mul_f32_e32 v78, 0xbfb8aa3b, v88
	v_exp_f32_e32 v78, v78
	v_fma_f32 v81, v53, v82, v81
	v_add_f32_e32 v80, v80, v81
	v_add_f32_e32 v82, v69, v80
	v_mul_f32_e32 v80, 0xbfb8aa3b, v82
	v_add_f32_e32 v78, 1.0, v78
	v_exp_f32_e32 v80, v80
	v_rcp_f32_e32 v78, v78
	v_mul_f32_e32 v77, v77, v85
	v_lshlrev_b32_e32 v81, 16, v79
	v_add_f32_e32 v85, 1.0, v80
	v_lshlrev_b32_e32 v80, 16, v87
	v_cvt_pk_bf16_f32 v77, v84, v77
	v_mul_f32_e32 v84, v88, v78
	v_lshlrev_b32_e32 v78, 16, v83
	v_pk_mul_f32 v[80:81], v[190:191], v[80:81]
	v_and_b32_e32 v79, 0xffff0000, v79
	v_fma_f32 v78, v54, v78, v81
	v_add_f32_e32 v78, v80, v78
	v_add_f32_e32 v80, v70, v78
	v_and_b32_e32 v78, 0xffff0000, v87
	v_and_b32_e32 v81, 0xffff0000, v83
	v_pk_mul_f32 v[78:79], v[62:63], v[78:79]
	v_rcp_f32_e32 v83, v85
	v_fma_f32 v79, v55, v81, v79
	v_add_f32_e32 v78, v78, v79
	v_add_f32_e32 v79, v71, v78
	v_mul_f32_e32 v78, 0xbfb8aa3b, v80
	v_exp_f32_e32 v78, v78
	v_mul_f32_e32 v81, 0xbfb8aa3b, v79
	v_exp_f32_e32 v81, v81
	v_cvt_pk_bf16_f32 v76, v90, v76
	v_add_f32_e32 v78, 1.0, v78
	v_rcp_f32_e32 v85, v78
	v_add_f32_e32 v78, 1.0, v81
	v_rcp_f32_e32 v81, v78
	v_mul_f32_e32 v78, v82, v83
	v_mul_f32_e32 v80, v80, v85
	v_cvt_pk_bf16_f32 v78, v84, v78
	v_mul_f32_e32 v79, v79, v81
	v_cvt_pk_bf16_f32 v79, v80, v79
	v_lshl_add_u64 v[80:81], v[200:201], 0, v[198:199]
	v_lshl_add_u64 v[200:201], v[200:201], 0, s[6:7]
	v_readlane_b32 s6, v253, 17
	v_readlane_b32 s7, v253, 18
	s_add_u32 s12, s12, s6
	s_addc_u32 s13, s13, s7
	v_readlane_b32 s6, v253, 19
	global_store_dwordx4 v[80:81], v[76:79], off
	v_readlane_b32 s7, v253, 20
	s_add_u32 s14, s14, s6
	v_mov_b64_e32 v[76:77], v[144:145]
	v_mov_b64_e32 v[88:89], v[128:129]
	s_addc_u32 s15, s15, s7
	s_andn2_b64 vcc, exec, s[16:17]
	v_mov_b64_e32 v[78:79], v[146:147]
	v_mov_b64_e32 v[90:91], v[130:131]
	v_mov_b64_e32 v[106:107], v[114:115]
	v_mov_b64_e32 v[156:157], v[100:101]
	v_mov_b64_e32 v[152:153], v[108:109]
	s_mov_b32 s18, s19
	v_mov_b32_e32 v120, v116
	v_mov_b32_e32 v121, v117
	v_mov_b32_e32 v122, v118
	v_mov_b32_e32 v123, v119
	v_mov_b32_e32 v92, v124
	v_mov_b32_e32 v93, v125
	v_mov_b32_e32 v94, v126
	v_mov_b32_e32 v95, v127
	v_mov_b32_e32 v80, v136
	v_mov_b32_e32 v81, v137
	v_mov_b32_e32 v82, v138
	v_mov_b32_e32 v83, v139
	v_mov_b32_e32 v140, v132
	v_mov_b32_e32 v141, v133
	v_mov_b32_e32 v142, v134
	v_mov_b32_e32 v143, v135
	v_mov_b32_e32 v96, v148
	v_mov_b32_e32 v97, v149
	v_mov_b32_e32 v98, v150
	v_mov_b32_e32 v99, v151
	v_mov_b32_e32 v84, v160
	v_mov_b32_e32 v85, v161
	v_mov_b32_e32 v86, v162
	v_mov_b32_e32 v87, v163
	s_cbranch_vccz .LBB0_815

; __device__ __forceinline__ unsigned pk2(float lo, float hi) { return cvtpk(lo, hi); }
; __device__ __forceinline__ void ph_prep(Frame& F, int layer) {
;     ...
;         for (int e = 0; e < 4; ++e) { const unsigned pq = (unsigned)__shfl_xor((int)qc[e], 4), pk = (unsigned)__shfl_xor((int)kc[e], 4);
;             const float c0 = e < 2 ? cs0[2 * e] : cs1[2 * e - 4], c1 = e < 2 ? cs0[2 * e + 1] : cs1[2 * e - 3], s0 = e < 2 ? sn0[2 * e] : sn1[2 * e - 4], s1 = e < 2 ? sn0[2 * e + 1] : sn1[2 * e - 3];
;             qo[e] = pk2(bflo(qc[e]) * c0 + bflo(pq) * s0, bfhi(qc[e]) * c1 + bfhi(pq) * s1); ko[e] = pk2(bflo(kc[e]) * c0 + bflo(pk) * s0, bfhi(kc[e]) * c1 + bfhi(pk) * s1); }
;         *(v4u*)(pAQ + (size_t)row * 512 + 8 * lane) = qo;
;         if (lane < 32) *(v4u*)(pAK + (size_t)row * 256 + 8 * lane) = ko;
.LBB0_813:
	ds_bpermute_b32 v168, v229, v156
	ds_bpermute_b32 v173, v229, v152
	v_lshlrev_b32_e32 v230, 16, v156
	v_and_b32_e32 v232, 0xffff0000, v156
	s_waitcnt lgkmcnt(1)
	v_lshlrev_b32_e32 v231, 16, v168
	v_and_b32_e32 v233, 0xffff0000, v168
	v_pk_mul_f32 v[230:231], v[212:213], v[230:231]
	s_waitcnt lgkmcnt(0)
	v_lshlrev_b32_e32 v220, 16, v173
	v_add_f32_e32 v156, v230, v231
	v_pk_mul_f32 v[230:231], v[210:211], v[232:233]
	v_mul_f32_e32 v213, v213, v220
	v_add_f32_e32 v168, v230, v231
	v_cvt_pk_bf16_f32 v156, v156, v168
	v_lshlrev_b32_e32 v168, 16, v152
	v_fmac_f32_e32 v213, v212, v168
	v_and_b32_e32 v168, 0xffff0000, v173
	ds_bpermute_b32 v173, v229, v157
	v_and_b32_e32 v152, 0xffff0000, v152
	v_mul_f32_e32 v168, v211, v168
	v_fmac_f32_e32 v168, v210, v152
	v_cvt_pk_bf16_f32 v152, v213, v168
	ds_bpermute_b32 v168, v229, v153
	v_lshlrev_b32_e32 v210, 16, v157
	s_waitcnt lgkmcnt(1)
	v_lshlrev_b32_e32 v211, 16, v173
	v_pk_mul_f32 v[210:211], v[208:209], v[210:211]
	s_nop 0
	v_add_f32_e32 v212, v210, v211
	v_and_b32_e32 v211, 0xffff0000, v173
	v_and_b32_e32 v210, 0xffff0000, v157
	v_pk_mul_f32 v[210:211], v[206:207], v[210:211]
	v_lshlrev_b32_e32 v173, 16, v153
	v_add_f32_e32 v157, v210, v211
	s_waitcnt lgkmcnt(0)
	v_lshlrev_b32_e32 v210, 16, v168
	v_mul_f32_e32 v209, v209, v210
	v_fmac_f32_e32 v209, v208, v173
	ds_bpermute_b32 v173, v229, v158
	v_and_b32_e32 v168, 0xffff0000, v168
	v_and_b32_e32 v153, 0xffff0000, v153
	v_mul_f32_e32 v168, v207, v168
	v_fmac_f32_e32 v168, v206, v153
	v_cvt_pk_bf16_f32 v153, v209, v168
	ds_bpermute_b32 v168, v229, v154
	v_lshlrev_b32_e32 v206, 16, v158
	s_waitcnt lgkmcnt(1)
	v_lshlrev_b32_e32 v207, 16, v173
	v_pk_mul_f32 v[206:207], v[164:165], v[206:207]
	v_cvt_pk_bf16_f32 v157, v212, v157
	s_nop 0
	v_add_f32_e32 v208, v206, v207
	v_and_b32_e32 v207, 0xffff0000, v173
	v_and_b32_e32 v206, 0xffff0000, v158
	v_pk_mul_f32 v[206:207], v[204:205], v[206:207]
	v_lshlrev_b32_e32 v173, 16, v154
	v_add_f32_e32 v158, v206, v207
	s_waitcnt lgkmcnt(0)
	v_lshlrev_b32_e32 v206, 16, v168
	v_mul_f32_e32 v165, v165, v206
	v_fmac_f32_e32 v165, v164, v173
	v_and_b32_e32 v164, 0xffff0000, v168
	ds_bpermute_b32 v168, v229, v159
	v_and_b32_e32 v154, 0xffff0000, v154
	v_mul_f32_e32 v164, v205, v164
	v_fmac_f32_e32 v164, v204, v154
	ds_bpermute_b32 v173, v229, v155
	v_cvt_pk_bf16_f32 v154, v165, v164
	v_lshlrev_b32_e32 v164, 16, v159
	s_waitcnt lgkmcnt(1)
	v_lshlrev_b32_e32 v165, 16, v168
	v_pk_mul_f32 v[164:165], v[166:167], v[164:165]
	v_cvt_pk_bf16_f32 v158, v208, v158
	s_nop 0
	v_add_f32_e32 v204, v164, v165
	v_and_b32_e32 v165, 0xffff0000, v168
	v_and_b32_e32 v164, 0xffff0000, v159
	v_pk_mul_f32 v[164:165], v[202:203], v[164:165]
	s_nop 0
	v_add_f32_e32 v159, v164, v165
	s_waitcnt lgkmcnt(0)
	v_lshlrev_b32_e32 v165, 16, v173
	v_lshlrev_b32_e32 v164, 16, v155
	v_mul_f32_e32 v165, v167, v165
	v_fmac_f32_e32 v165, v166, v164
	v_and_b32_e32 v164, 0xffff0000, v173
	v_and_b32_e32 v155, 0xffff0000, v155
	v_mul_f32_e32 v164, v203, v164
	v_fmac_f32_e32 v164, v202, v155
	v_cvt_pk_bf16_f32 v155, v165, v164
	v_lshl_add_u64 v[164:165], s[14:15], 0, v[198:199]
	v_cvt_pk_bf16_f32 v159, v204, v159
	global_store_dwordx4 v[164:165], v[156:159], off
	s_and_saveexec_b64 s[6:7], s[4:5]
	s_cbranch_execz .LBB0_795
	v_lshl_add_u64 v[156:157], s[2:3], 0, v[198:199]
	global_store_dwordx4 v[156:157], v[152:155], off
	s_branch .LBB0_795
